# selection loop: list/selw LDS reads hoisted to iteration top, single lgkm wait
# speedup vs baseline: 1.0265x; 1.0023x over previous
; __device__ __forceinline__ void nsa_unit(const Params& p, int bg, int jq, LAS unsigned char* lds, int wave, int lane, bool build_lut) {
;     ...
;                 const int nb[2] = {n0, n1};
;                 const bool real1 = (2 * it + 1) < cnt;
; #pragma unroll
;                 for (int u = 0; u < 2; ++u)
; #pragma unroll
;                     for (int i = 0; i < 4; ++i) { const l64x2 t = *(const l64x2*)(vs8 + (size_t)nb[u] * 4096 + i * 1024 + lane * 16); v8[u][2 * i] = t[0]; v8[u][2 * i + 1] = t[1]; }
;                 bool ok[2];
;                 ok[0] = (selw[(grp * 4 + q4) * 8 + (nb[0] >> 5)] >> (nb[0] & 31)) & 1u;
;                 ok[1] = real1 && ((selw[(grp * 4 + q4) * 8 + (nb[1] >> 5)] >> (nb[1] & 31)) & 1u);
;                 const int bmax = real1 ? max(nb[0], nb[1]) : nb[0];
;                 const bool fast = (tq0g - 64 * bmax - 63) >= 128;
;                 const bool fresh = m < -1e29f;
;                 const float mref = fresh ? 0.f : m;
;                 float ini[2];
;                 ini[0] = fast ? (ok[0] ? -(mref - lutfar16 - 6.0f) : NEG_INF) : 0.f;
;                 ini[1] = fast ? (ok[1] ? -(mref - lutfar16 - 6.0f) : NEG_INF) : 0.f;
;                 f32x4 sc[2][4];
; #pragma unroll
;                 for (int u = 0; u < 2; ++u)
; #pragma unroll
;                     for (int kt = 0; kt < 4; ++kt) {
;                         sc[u][kt] = __builtin_amdgcn_mfma_f32_16x16x32_fp8_fp8(k8[u][2 * kt], q8[0], (f32x4){ini[u], ini[u], ini[u], ini[u]}, 0, 0, 0);
;                         sc[u][kt] = __builtin_amdgcn_mfma_f32_16x16x32_fp8_fp8(k8[u][2 * kt + 1], q8[1], sc[u][kt], 0, 0, 0);
;                     }
;                 if (it + 1 < npair) {
;                     n0 = __builtin_amdgcn_readfirstlane(list[lbase + 2 * it + 2]); n1 = __builtin_amdgcn_readfirstlane(list[lbase + 2 * it + 3]);
; #pragma unroll
;                     for (int i = 0; i < 4; ++i) { const l64x2 t0 = *(const l64x2*)(ks8 + (size_t)n0 * 4096 + i * 1024 + lane * 16), t1 = *(const l64x2*)(ks8 + (size_t)n1 * 4096 + i * 1024 + lane * 16);
;                         k8[0][2 * i] = t0[0]; k8[0][2 * i + 1] = t0[1]; k8[1][2 * i] = t1[0]; k8[1][2 * i + 1] = t1[1]; }
;                 }
.LBB0_1200:
	v_mov_b32_e32 v238, s43
	ds_read_b64 v[238:239], v238
	s_ashr_i32 s6, s22, 5
	v_lshl_add_u32 v1, s6, 2, v167
	ds_read_b32 v1, v1 offset:8192
	s_ashr_i32 s6, s8, 5
	v_lshl_add_u32 v2, s6, 2, v167
	ds_read_b32 v240, v2 offset:8192
	s_ashr_i32 s23, s22, 31
	s_lshl_b64 s[4:5], s[22:23], 12
	s_ashr_i32 s9, s8, 31
	v_lshl_add_u64 v[2:3], v[150:151], 0, s[4:5]
	s_lshl_b64 s[4:5], s[8:9], 12
	global_load_dwordx4 v[84:87], v[2:3], off
	global_load_dwordx4 v[80:83], v[2:3], off offset:1024
	global_load_dwordx4 v[76:79], v[2:3], off offset:2048
	global_load_dwordx4 v[72:75], v[2:3], off offset:3072
	v_lshl_add_u64 v[2:3], v[150:151], 0, s[4:5]
	global_load_dwordx4 v[68:71], v[2:3], off
	global_load_dwordx4 v[64:67], v[2:3], off offset:1024
	global_load_dwordx4 v[60:63], v[2:3], off offset:2048
	global_load_dwordx4 v[56:59], v[2:3], off offset:3072
	s_cmp_lt_u32 s40, s38
	s_cselect_b64 s[4:5], -1, 0
	s_waitcnt lgkmcnt(0)
	v_lshrrev_b32_e32 v2, s8, v240
	v_and_b32_e32 v2, 1, v2
	v_cmp_eq_u32_e32 vcc, 1, v2
	s_and_b64 s[20:21], vcc, s[4:5]
.LBB0_1202:
	s_max_i32 s6, s22, s8
	s_and_b64 s[4:5], s[4:5], exec
	s_cselect_b32 s4, s6, s22
	s_lshl_b32 s4, s4, 6
	s_sub_i32 s4, s39, s4
	s_cmpk_lt_i32 s4, 0xbf
	s_cselect_b64 s[24:25], -1, 0
	s_cmpk_gt_i32 s4, 0xbe
	v_cmp_ngt_f32_e64 s[4:5], s93, v157
	s_waitcnt lgkmcnt(0)
	v_lshrrev_b32_e32 v1, s22, v1
	v_and_b32_e32 v1, 1, v1
	v_cndmask_b32_e64 v156, 0, v157, s[4:5]
	v_sub_f32_e32 v2, v156, v161
	v_add_f32_e32 v2, 0xc0c00000, v2
	v_cmp_eq_u32_e64 s[6:7], 1, v1
	s_cselect_b64 vcc, -1, 0
	s_add_i32 s44, s44, 1
	v_cndmask_b32_e64 v1, v230, -v2, s[6:7]
	v_cndmask_b32_e32 v88, 0, v1, vcc
	v_mov_b32_e32 v89, v88
	v_mov_b32_e32 v90, v88
	v_mov_b32_e32 v91, v88
	v_cndmask_b32_e64 v1, v230, -v2, s[20:21]
	v_cndmask_b32_e32 v120, 0, v1, vcc
	s_waitcnt vmcnt(8)
	v_mfma_f32_16x16x32_fp8_fp8 v[92:95], v[16:17], v[152:153], v[88:91]
	v_mov_b32_e32 v121, v120
	v_mov_b32_e32 v122, v120
	v_mov_b32_e32 v123, v120
	v_mfma_f32_16x16x32_fp8_fp8 v[116:119], v[18:19], v[154:155], v[92:95]
	s_cmp_ge_u32 s44, s41
	s_mov_b32 s16, s22
	s_mov_b32 s18, s8
	v_mfma_f32_16x16x32_fp8_fp8 v[92:95], v[28:29], v[152:153], v[88:91]
	v_mfma_f32_16x16x32_fp8_fp8 v[108:111], v[30:31], v[154:155], v[92:95]
	v_mfma_f32_16x16x32_fp8_fp8 v[92:95], v[20:21], v[152:153], v[88:91]
	v_mfma_f32_16x16x32_fp8_fp8 v[88:91], v[36:37], v[152:153], v[88:91]
	v_mfma_f32_16x16x32_fp8_fp8 v[100:103], v[38:39], v[154:155], v[88:91]
	v_mfma_f32_16x16x32_fp8_fp8 v[88:91], v[4:5], v[152:153], v[120:123]
	v_mfma_f32_16x16x32_fp8_fp8 v[112:115], v[6:7], v[154:155], v[88:91]
	v_mfma_f32_16x16x32_fp8_fp8 v[88:91], v[12:13], v[152:153], v[120:123]
	v_mfma_f32_16x16x32_fp8_fp8 v[104:107], v[14:15], v[154:155], v[88:91]
	v_mfma_f32_16x16x32_fp8_fp8 v[88:91], v[8:9], v[152:153], v[120:123]
	v_mfma_f32_16x16x32_fp8_fp8 v[96:99], v[22:23], v[154:155], v[92:95]
	v_mfma_f32_16x16x32_fp8_fp8 v[92:95], v[10:11], v[154:155], v[88:91]
	v_mfma_f32_16x16x32_fp8_fp8 v[88:91], v[32:33], v[152:153], v[120:123]
	v_mfma_f32_16x16x32_fp8_fp8 v[88:91], v[34:35], v[154:155], v[88:91]
	s_cbranch_scc1 .LBB0_1204
	v_readfirstlane_b32 s16, v238
	v_readfirstlane_b32 s18, v239
	s_ashr_i32 s17, s16, 31
	s_lshl_b64 s[46:47], s[16:17], 12
	s_ashr_i32 s19, s18, 31
	v_lshl_add_u64 v[2:3], v[148:149], 0, s[46:47]
	s_lshl_b64 s[46:47], s[18:19], 12
	v_lshl_add_u64 v[32:33], v[148:149], 0, s[46:47]
	global_load_dwordx4 v[16:19], v[2:3], off
	global_load_dwordx4 v[4:7], v[32:33], off
	global_load_dwordx4 v[28:31], v[2:3], off offset:1024
	global_load_dwordx4 v[12:15], v[32:33], off offset:1024
	global_load_dwordx4 v[20:23], v[2:3], off offset:2048
	global_load_dwordx4 v[8:11], v[32:33], off offset:2048
	global_load_dwordx4 v[36:39], v[2:3], off offset:3072
	s_nop 0
	global_load_dwordx4 v[32:35], v[32:33], off offset:3072
